# v31 with the PREPA lora part's previous-row load and mu loads in flight together (one wait instead of two serialised round trips)
# baseline (speedup 1.0000x reference)
.LBB0_518:
	s_or_b64 exec, exec, s[20:21]
	s_and_saveexec_b64 s[18:19], s[40:41]
	s_xor_b64 s[20:21], exec, s[18:19]
	s_cbranch_execz .LBB0_520
	global_load_dwordx4 v[46:49], v[18:19], off offset:-1152
	global_load_dwordx4 v[50:53], v[18:19], off offset:-1136
	s_andn2_saveexec_b64 s[20:21], s[20:21]
	s_cbranch_execnz .LBB0_521
	s_branch .LBB0_522

.LBB0_521:
	global_load_dwordx4 v[46:49], v[20:21], off
	global_load_dwordx4 v[50:53], v[20:21], off offset:16
.LBB0_522:
	s_or_b64 exec, exec, s[20:21]
	s_waitcnt vmcnt(0)
	v_and_b32_e32 v54, 0xfff, v24
	v_cmp_ne_u32_e32 vcc, 0, v54
	s_and_saveexec_b64 s[18:19], vcc
	v_lshlrev_b32_e32 v26, 16, v4
	v_and_b32_e32 v28, 0xffff0000, v4
	v_lshlrev_b32_e32 v27, 16, v5
	v_and_b32_e32 v30, 0xffff0000, v5
	v_lshlrev_b32_e32 v29, 16, v6
	v_and_b32_e32 v32, 0xffff0000, v6
	v_lshlrev_b32_e32 v31, 16, v7
	v_and_b32_e32 v33, 0xffff0000, v7
	s_or_b64 exec, exec, s[18:19]
	v_lshlrev_b32_e32 v34, 16, v0
	v_and_b32_e32 v35, 0xffff0000, v0
	v_lshlrev_b32_e32 v38, 16, v1
	v_and_b32_e32 v39, 0xffff0000, v1
	v_lshlrev_b32_e32 v40, 16, v2
	v_and_b32_e32 v41, 0xffff0000, v2
	v_lshlrev_b32_e32 v0, 16, v3
	v_and_b32_e32 v1, 0xffff0000, v3
	v_sub_f32_e32 v43, v28, v35
	v_sub_f32_e32 v42, v26, v34
	v_sub_f32_e32 v45, v30, v39
	v_sub_f32_e32 v44, v27, v38
	v_sub_f32_e32 v3, v32, v41
	v_sub_f32_e32 v2, v29, v40
	v_sub_f32_e32 v27, v33, v1
	v_sub_f32_e32 v26, v31, v0
	v_pk_fma_f32 v[0:1], v[26:27], v[52:53], v[0:1]
	v_pk_fma_f32 v[2:3], v[2:3], v[50:51], v[40:41]
	v_pk_fma_f32 v[6:7], v[44:45], v[48:49], v[38:39]
	v_pk_fma_f32 v[4:5], v[42:43], v[46:47], v[34:35]
	s_and_saveexec_b64 s[18:19], s[42:43]
	s_xor_b64 s[20:21], exec, s[18:19]
	s_cbranch_execz .LBB0_526
	s_and_saveexec_b64 s[22:23], s[44:45]
	s_cbranch_execz .LBB0_525
	v_mul_f32_e32 v4, 0xbfb8aa3b, v4
	v_mul_f32_e32 v5, 0xbfb8aa3b, v5
	v_mul_f32_e32 v6, 0xbfb8aa3b, v6
	v_mul_f32_e32 v7, 0xbfb8aa3b, v7
	v_mul_f32_e32 v2, 0xbfb8aa3b, v2
	v_mul_f32_e32 v3, 0xbfb8aa3b, v3
	v_mul_f32_e32 v0, 0xbfb8aa3b, v0
	v_mul_f32_e32 v1, 0xbfb8aa3b, v1
	v_exp_f32_e32 v4, v4
	v_exp_f32_e32 v5, v5
	v_exp_f32_e32 v6, v6
	v_exp_f32_e32 v7, v7
	v_exp_f32_e32 v2, v2
	v_exp_f32_e32 v3, v3
	v_exp_f32_e32 v0, v0
	v_exp_f32_e32 v1, v1
	v_add_f32_e32 v4, 1.0, v4
	v_add_f32_e32 v5, 1.0, v5
	v_add_f32_e32 v6, 1.0, v6
	v_add_f32_e32 v7, 1.0, v7
	v_add_f32_e32 v2, 1.0, v2
	v_add_f32_e32 v3, 1.0, v3
	v_add_f32_e32 v0, 1.0, v0
	v_add_f32_e32 v1, 1.0, v1
	v_rcp_f32_e32 v4, v4
	v_rcp_f32_e32 v5, v5
	v_rcp_f32_e32 v6, v6
	v_rcp_f32_e32 v7, v7
	v_rcp_f32_e32 v2, v2
	v_rcp_f32_e32 v3, v3
	v_rcp_f32_e32 v0, v0
	v_rcp_f32_e32 v1, v1
